# k11 with SwiGLU per-row scale via LDS table (one ssq half-row per thread + DPP, one barrier), 32 -> 2 ssq loads per lane per tile
# speedup vs baseline: 1.0263x; 1.0263x over previous
; __device__ __forceinline__ unsigned cvtpk(float lo, float hi) { f32x2_t v = {lo, hi}; bf16x2_t b = __builtin_convertvector(v, bf16x2_t); return __builtin_bit_cast(unsigned, b); }
;     __device__ __forceinline__ void operator()(const f32x4 (&acc)[2][2][4][2], const Unit& u, int wr, int wc, int fr, int fq) const {
;         const int row0 = u.pm * BM + wr * 64 + fr, col0 = u.pn * 128 + wc * 32 + 8 * fq;
; #pragma unroll
;         for (int ai = 0; ai < 2; ++ai)
; #pragma unroll
;             for (int m = 0; m < 4; ++m) {
;                 const int row = row0 + ai * HALF + m * 16;
;                 const float rs = 1.0f / sqrtf(ssq_sum(ssq + (size_t)row * 16) * (1.0f / DM) + EPS);
;                 float hv[8];
; #pragma unroll
;                 for (int n = 0; n < 2; ++n)
; #pragma unroll
;                     for (int e = 0; e < 4; ++e) {
;                         const float gg = acc[ai][0][m][n][e] * rs, uu = acc[ai][1][m][n][e] * rs;
;                         const float den = 1.0f + __builtin_amdgcn_exp2f(-gg * LOG2E);
;                         hv[n * 4 + e] = gg * uu * __builtin_amdgcn_rcpf(den);
;                     }
;                 u32x4 w; w.x = cvtpk(hv[0], hv[1]); w.y = cvtpk(hv[2], hv[3]); w.z = cvtpk(hv[4], hv[5]); w.w = cvtpk(hv[6], hv[7]);
;                 *(u32x4*)(H + (size_t)row * DFF + col0) = w;
.LBB0_244:
	v_readlane_b32 s9, v254, 7
	v_mbcnt_lo_u32_b32 v144, -1, 0
	v_mbcnt_hi_u32_b32 v144, -1, v144
	v_lshrrev_b32_e32 v145, 1, v144
	v_lshl_add_u32 v145, s9, 5, v145
	v_and_b32_e32 v146, 1, v144
	v_lshl_add_u32 v147, s8, 8, v145
	v_lshlrev_b32_e32 v147, 6, v147
	v_lshl_add_u32 v147, v146, 5, v147
	global_load_dwordx4 v[160:163], v147, s[14:15]
	global_load_dwordx4 v[164:167], v147, s[14:15] offset:16
	v_lshl_add_u32 v148, s8, 8, v152
	v_mov_b64_e32 v[146:147], s[16:17]
	v_mad_i64_i32 v[176:177], s[8:9], v148, s56, v[146:147]
	v_lshl_or_b32 v150, s2, 7, v154
	v_mov_b32_e32 v151, 0
	v_lshlrev_b64 v[150:151], 1, v[150:151]
	v_lshl_add_u64 v[176:177], v[176:177], 0, v[150:151]
	v_lshlrev_b32_e32 v145, 3, v145
	v_add_u32_e32 v145, 0x20100, v145
	v_lshlrev_b32_e32 v146, 3, v152
	v_add_u32_e32 v146, 0x20100, v146
	s_mov_b32 s9, 0
	s_waitcnt vmcnt(0)
	v_pk_add_f32 v[160:161], v[160:161], v[162:163]
	v_pk_add_f32 v[164:165], v[164:165], v[166:167]
	v_pk_add_f32 v[160:161], v[160:161], v[164:165]
	v_add_f32_e32 v160, v160, v161
	s_nop 1
	v_add_f32_dpp v160, v160, v160 quad_perm:[1,0,3,2] row_mask:0xf bank_mask:0xf
	v_fmamk_f32 v160, v160, 0x3a800000, v158
	v_rsq_f32_e32 v161, v160
	s_nop 0
	v_mul_f32_e32 v161, 0xbfb8aa3b, v161
	ds_write_b64 v145, v[160:161]
	s_waitcnt lgkmcnt(0)
	s_barrier
	ds_read_b64 v[160:161], v146 offset:0
	ds_read_b64 v[162:163], v146 offset:128
	ds_read_b64 v[164:165], v146 offset:256
	ds_read_b64 v[166:167], v146 offset:384
	ds_read_b64 v[168:169], v146 offset:1024
	ds_read_b64 v[170:171], v146 offset:1152
	ds_read_b64 v[172:173], v146 offset:1280
	ds_read_b64 v[174:175], v146 offset:1408
	v_pk_mul_f32 v[116:117], v[124:125], v[116:117]
	v_pk_mul_f32 v[118:119], v[126:127], v[118:119]
	v_pk_mul_f32 v[112:113], v[120:121], v[112:113]
	v_pk_mul_f32 v[114:115], v[122:123], v[114:115]
	s_waitcnt lgkmcnt(7)
	v_mov_b32_e32 v150, v161
	v_pk_mul_f32 v[124:125], v[124:125], v[150:151] op_sel_hi:[1,0]
	v_pk_mul_f32 v[126:127], v[126:127], v[150:151] op_sel_hi:[1,0]
	v_pk_mul_f32 v[120:121], v[120:121], v[150:151] op_sel_hi:[1,0]
	v_pk_mul_f32 v[122:123], v[122:123], v[150:151] op_sel_hi:[1,0]
	v_exp_f32_e32 v124, v124
	v_exp_f32_e32 v125, v125
	v_exp_f32_e32 v126, v126
	v_exp_f32_e32 v127, v127
	v_exp_f32_e32 v120, v120
	v_exp_f32_e32 v121, v121
	v_exp_f32_e32 v122, v122
	v_exp_f32_e32 v123, v123
	v_fma_f32 v124, v124, v160, v160
	v_fma_f32 v125, v125, v160, v160
	v_fma_f32 v126, v126, v160, v160
	v_fma_f32 v127, v127, v160, v160
	v_fma_f32 v120, v120, v160, v160
	v_fma_f32 v121, v121, v160, v160
	v_fma_f32 v122, v122, v160, v160
	v_fma_f32 v123, v123, v160, v160
	v_rcp_f32_e32 v124, v124
	v_rcp_f32_e32 v125, v125
	v_rcp_f32_e32 v126, v126
	v_rcp_f32_e32 v127, v127
	v_rcp_f32_e32 v120, v120
	v_rcp_f32_e32 v121, v121
	v_rcp_f32_e32 v122, v122
	v_rcp_f32_e32 v123, v123
	v_pk_mul_f32 v[116:117], v[116:117], v[124:125]
	v_pk_mul_f32 v[118:119], v[118:119], v[126:127]
	v_pk_mul_f32 v[112:113], v[112:113], v[120:121]
	v_pk_mul_f32 v[114:115], v[114:115], v[122:123]
	v_cvt_pk_bf16_f32 v124, v116, v117
	v_cvt_pk_bf16_f32 v125, v118, v119
	v_cvt_pk_bf16_f32 v126, v112, v113
	v_cvt_pk_bf16_f32 v127, v114, v115
	global_store_dwordx4 v[176:177], v[124:127], off
	v_pk_mul_f32 v[100:101], v[108:109], v[100:101]
	v_pk_mul_f32 v[102:103], v[110:111], v[102:103]
	v_pk_mul_f32 v[96:97], v[104:105], v[96:97]
	v_pk_mul_f32 v[98:99], v[106:107], v[98:99]
	s_waitcnt lgkmcnt(6)
	v_mov_b32_e32 v150, v163
	v_pk_mul_f32 v[108:109], v[108:109], v[150:151] op_sel_hi:[1,0]
	v_pk_mul_f32 v[110:111], v[110:111], v[150:151] op_sel_hi:[1,0]
	v_pk_mul_f32 v[104:105], v[104:105], v[150:151] op_sel_hi:[1,0]
	v_pk_mul_f32 v[106:107], v[106:107], v[150:151] op_sel_hi:[1,0]
	v_exp_f32_e32 v108, v108
	v_exp_f32_e32 v109, v109
	v_exp_f32_e32 v110, v110
	v_exp_f32_e32 v111, v111
	v_exp_f32_e32 v104, v104
	v_exp_f32_e32 v105, v105
	v_exp_f32_e32 v106, v106
	v_exp_f32_e32 v107, v107
	v_fma_f32 v108, v108, v162, v162
	v_fma_f32 v109, v109, v162, v162
	v_fma_f32 v110, v110, v162, v162
	v_fma_f32 v111, v111, v162, v162
	v_fma_f32 v104, v104, v162, v162
	v_fma_f32 v105, v105, v162, v162
	v_fma_f32 v106, v106, v162, v162
	v_fma_f32 v107, v107, v162, v162
	v_rcp_f32_e32 v108, v108
	v_rcp_f32_e32 v109, v109
	v_rcp_f32_e32 v110, v110
	v_rcp_f32_e32 v111, v111
	v_rcp_f32_e32 v104, v104
	v_rcp_f32_e32 v105, v105
	v_rcp_f32_e32 v106, v106
	v_rcp_f32_e32 v107, v107
	s_mov_b32 s8, 0x16000
	v_pk_mul_f32 v[100:101], v[100:101], v[108:109]
	v_pk_mul_f32 v[102:103], v[102:103], v[110:111]
	v_pk_mul_f32 v[96:97], v[96:97], v[104:105]
	v_pk_mul_f32 v[98:99], v[98:99], v[106:107]
	v_cvt_pk_bf16_f32 v108, v100, v101
	v_cvt_pk_bf16_f32 v109, v102, v103
	v_cvt_pk_bf16_f32 v110, v96, v97
	v_cvt_pk_bf16_f32 v111, v98, v99
	v_lshl_add_u64 v[178:179], v[176:177], 0, s[8:9]
	global_store_dwordx4 v[178:179], v[108:111], off
	v_pk_mul_f32 v[84:85], v[92:93], v[84:85]
	v_pk_mul_f32 v[86:87], v[94:95], v[86:87]
	v_pk_mul_f32 v[80:81], v[88:89], v[80:81]
	v_pk_mul_f32 v[82:83], v[90:91], v[82:83]
	s_waitcnt lgkmcnt(5)
; __device__ __forceinline__ unsigned cvtpk(float lo, float hi) { f32x2_t v = {lo, hi}; bf16x2_t b = __builtin_convertvector(v, bf16x2_t); return __builtin_bit_cast(unsigned, b); }
;     __device__ __forceinline__ void operator()(const f32x4 (&acc)[2][2][4][2], const Unit& u, int wr, int wc, int fr, int fq) const {
;     ...
;             for (int m = 0; m < 4; ++m) {
;                 const int row = row0 + ai * HALF + m * 16;
;                 const float rs = 1.0f / sqrtf(ssq_sum(ssq + (size_t)row * 16) * (1.0f / DM) + EPS);
;                 float hv[8];
; #pragma unroll
;                 for (int n = 0; n < 2; ++n)
; #pragma unroll
;                     for (int e = 0; e < 4; ++e) {
;                         const float gg = acc[ai][0][m][n][e] * rs, uu = acc[ai][1][m][n][e] * rs;
;                         const float den = 1.0f + __builtin_amdgcn_exp2f(-gg * LOG2E);
;                         hv[n * 4 + e] = gg * uu * __builtin_amdgcn_rcpf(den);
;                     }
;                 u32x4 w; w.x = cvtpk(hv[0], hv[1]); w.y = cvtpk(hv[2], hv[3]); w.z = cvtpk(hv[4], hv[5]); w.w = cvtpk(hv[6], hv[7]);
;                 *(u32x4*)(H + (size_t)row * DFF + col0) = w;
	v_mov_b32_e32 v150, v165
	v_pk_mul_f32 v[92:93], v[92:93], v[150:151] op_sel_hi:[1,0]
	v_pk_mul_f32 v[94:95], v[94:95], v[150:151] op_sel_hi:[1,0]
	v_pk_mul_f32 v[88:89], v[88:89], v[150:151] op_sel_hi:[1,0]
	v_pk_mul_f32 v[90:91], v[90:91], v[150:151] op_sel_hi:[1,0]
	v_exp_f32_e32 v92, v92
	v_exp_f32_e32 v93, v93
	v_exp_f32_e32 v94, v94
	v_exp_f32_e32 v95, v95
	v_exp_f32_e32 v88, v88
	v_exp_f32_e32 v89, v89
	v_exp_f32_e32 v90, v90
	v_exp_f32_e32 v91, v91
	v_fma_f32 v92, v92, v164, v164
	v_fma_f32 v93, v93, v164, v164
	v_fma_f32 v94, v94, v164, v164
	v_fma_f32 v95, v95, v164, v164
	v_fma_f32 v88, v88, v164, v164
	v_fma_f32 v89, v89, v164, v164
	v_fma_f32 v90, v90, v164, v164
	v_fma_f32 v91, v91, v164, v164
	v_rcp_f32_e32 v92, v92
	v_rcp_f32_e32 v93, v93
	v_rcp_f32_e32 v94, v94
	v_rcp_f32_e32 v95, v95
	v_rcp_f32_e32 v88, v88
	v_rcp_f32_e32 v89, v89
	v_rcp_f32_e32 v90, v90
	v_rcp_f32_e32 v91, v91
	s_mov_b32 s8, 0x2c000
	v_pk_mul_f32 v[84:85], v[84:85], v[92:93]
	v_pk_mul_f32 v[86:87], v[86:87], v[94:95]
	v_pk_mul_f32 v[80:81], v[80:81], v[88:89]
	v_pk_mul_f32 v[82:83], v[82:83], v[90:91]
	v_cvt_pk_bf16_f32 v92, v84, v85
	v_cvt_pk_bf16_f32 v93, v86, v87
	v_cvt_pk_bf16_f32 v94, v80, v81
	v_cvt_pk_bf16_f32 v95, v82, v83
	v_lshl_add_u64 v[178:179], v[176:177], 0, s[8:9]
	global_store_dwordx4 v[178:179], v[92:95], off
	v_pk_mul_f32 v[68:69], v[76:77], v[68:69]
	v_pk_mul_f32 v[70:71], v[78:79], v[70:71]
	v_pk_mul_f32 v[64:65], v[72:73], v[64:65]
	v_pk_mul_f32 v[66:67], v[74:75], v[66:67]
	s_waitcnt lgkmcnt(4)
	v_mov_b32_e32 v150, v167
	v_pk_mul_f32 v[76:77], v[76:77], v[150:151] op_sel_hi:[1,0]
	v_pk_mul_f32 v[78:79], v[78:79], v[150:151] op_sel_hi:[1,0]
	v_pk_mul_f32 v[72:73], v[72:73], v[150:151] op_sel_hi:[1,0]
	v_pk_mul_f32 v[74:75], v[74:75], v[150:151] op_sel_hi:[1,0]
	v_exp_f32_e32 v76, v76
	v_exp_f32_e32 v77, v77
	v_exp_f32_e32 v78, v78
	v_exp_f32_e32 v79, v79
	v_exp_f32_e32 v72, v72
	v_exp_f32_e32 v73, v73
	v_exp_f32_e32 v74, v74
	v_exp_f32_e32 v75, v75
	v_fma_f32 v76, v76, v166, v166
	v_fma_f32 v77, v77, v166, v166
	v_fma_f32 v78, v78, v166, v166
	v_fma_f32 v79, v79, v166, v166
	v_fma_f32 v72, v72, v166, v166
	v_fma_f32 v73, v73, v166, v166
	v_fma_f32 v74, v74, v166, v166
	v_fma_f32 v75, v75, v166, v166
	v_rcp_f32_e32 v76, v76
	v_rcp_f32_e32 v77, v77
	v_rcp_f32_e32 v78, v78
	v_rcp_f32_e32 v79, v79
	v_rcp_f32_e32 v72, v72
	v_rcp_f32_e32 v73, v73
	v_rcp_f32_e32 v74, v74
	v_rcp_f32_e32 v75, v75
	s_mov_b32 s8, 0x42000
	v_pk_mul_f32 v[68:69], v[68:69], v[76:77]
	v_pk_mul_f32 v[70:71], v[70:71], v[78:79]
	v_pk_mul_f32 v[64:65], v[64:65], v[72:73]
	v_pk_mul_f32 v[66:67], v[66:67], v[74:75]
	v_cvt_pk_bf16_f32 v76, v68, v69
	v_cvt_pk_bf16_f32 v77, v70, v71
	v_cvt_pk_bf16_f32 v78, v64, v65
	v_cvt_pk_bf16_f32 v79, v66, v67
	v_lshl_add_u64 v[178:179], v[176:177], 0, s[8:9]
	global_store_dwordx4 v[178:179], v[76:79], off
	v_pk_mul_f32 v[52:53], v[60:61], v[52:53]
	v_pk_mul_f32 v[54:55], v[62:63], v[54:55]
	v_pk_mul_f32 v[48:49], v[56:57], v[48:49]
	v_pk_mul_f32 v[50:51], v[58:59], v[50:51]
	s_waitcnt lgkmcnt(3)
	v_mov_b32_e32 v150, v169
	v_pk_mul_f32 v[60:61], v[60:61], v[150:151] op_sel_hi:[1,0]
	v_pk_mul_f32 v[62:63], v[62:63], v[150:151] op_sel_hi:[1,0]
	v_pk_mul_f32 v[56:57], v[56:57], v[150:151] op_sel_hi:[1,0]
	v_pk_mul_f32 v[58:59], v[58:59], v[150:151] op_sel_hi:[1,0]
	v_exp_f32_e32 v60, v60
	v_exp_f32_e32 v61, v61
	v_exp_f32_e32 v62, v62
	v_exp_f32_e32 v63, v63
	v_exp_f32_e32 v56, v56
	v_exp_f32_e32 v57, v57
	v_exp_f32_e32 v58, v58
	v_exp_f32_e32 v59, v59
	v_fma_f32 v60, v60, v168, v168
	v_fma_f32 v61, v61, v168, v168
	v_fma_f32 v62, v62, v168, v168
	v_fma_f32 v63, v63, v168, v168
	v_fma_f32 v56, v56, v168, v168
	v_fma_f32 v57, v57, v168, v168
	v_fma_f32 v58, v58, v168, v168
	v_fma_f32 v59, v59, v168, v168
	v_rcp_f32_e32 v60, v60
	v_rcp_f32_e32 v61, v61
	v_rcp_f32_e32 v62, v62
	v_rcp_f32_e32 v63, v63
	v_rcp_f32_e32 v56, v56
	v_rcp_f32_e32 v57, v57
	v_rcp_f32_e32 v58, v58
	v_rcp_f32_e32 v59, v59
	s_mov_b32 s8, 0xb0000
	v_pk_mul_f32 v[52:53], v[52:53], v[60:61]
	v_pk_mul_f32 v[54:55], v[54:55], v[62:63]
	v_pk_mul_f32 v[48:49], v[48:49], v[56:57]
	v_pk_mul_f32 v[50:51], v[50:51], v[58:59]
	v_cvt_pk_bf16_f32 v60, v52, v53
	v_cvt_pk_bf16_f32 v61, v54, v55
	v_cvt_pk_bf16_f32 v62, v48, v49
	v_cvt_pk_bf16_f32 v63, v50, v51
	v_lshl_add_u64 v[178:179], v[176:177], 0, s[8:9]
	global_store_dwordx4 v[178:179], v[60:63], off
	v_pk_mul_f32 v[36:37], v[44:45], v[36:37]
	v_pk_mul_f32 v[38:39], v[46:47], v[38:39]
	v_pk_mul_f32 v[32:33], v[40:41], v[32:33]
	v_pk_mul_f32 v[34:35], v[42:43], v[34:35]
	s_waitcnt lgkmcnt(2)
; __device__ __forceinline__ unsigned cvtpk(float lo, float hi) { f32x2_t v = {lo, hi}; bf16x2_t b = __builtin_convertvector(v, bf16x2_t); return __builtin_bit_cast(unsigned, b); }
;     __device__ __forceinline__ void operator()(const f32x4 (&acc)[2][2][4][2], const Unit& u, int wr, int wc, int fr, int fq) const {
;     ...
;             for (int m = 0; m < 4; ++m) {
;                 const int row = row0 + ai * HALF + m * 16;
;                 const float rs = 1.0f / sqrtf(ssq_sum(ssq + (size_t)row * 16) * (1.0f / DM) + EPS);
;                 float hv[8];
; #pragma unroll
;                 for (int n = 0; n < 2; ++n)
; #pragma unroll
;                     for (int e = 0; e < 4; ++e) {
;                         const float gg = acc[ai][0][m][n][e] * rs, uu = acc[ai][1][m][n][e] * rs;
;                         const float den = 1.0f + __builtin_amdgcn_exp2f(-gg * LOG2E);
;                         hv[n * 4 + e] = gg * uu * __builtin_amdgcn_rcpf(den);
;                     }
;                 u32x4 w; w.x = cvtpk(hv[0], hv[1]); w.y = cvtpk(hv[2], hv[3]); w.z = cvtpk(hv[4], hv[5]); w.w = cvtpk(hv[6], hv[7]);
;                 *(u32x4*)(H + (size_t)row * DFF + col0) = w;
	v_mov_b32_e32 v150, v171
	v_pk_mul_f32 v[44:45], v[44:45], v[150:151] op_sel_hi:[1,0]
	v_pk_mul_f32 v[46:47], v[46:47], v[150:151] op_sel_hi:[1,0]
	v_pk_mul_f32 v[40:41], v[40:41], v[150:151] op_sel_hi:[1,0]
	v_pk_mul_f32 v[42:43], v[42:43], v[150:151] op_sel_hi:[1,0]
	v_exp_f32_e32 v44, v44
	v_exp_f32_e32 v45, v45
	v_exp_f32_e32 v46, v46
	v_exp_f32_e32 v47, v47
	v_exp_f32_e32 v40, v40
	v_exp_f32_e32 v41, v41
	v_exp_f32_e32 v42, v42
	v_exp_f32_e32 v43, v43
	v_fma_f32 v44, v44, v170, v170
	v_fma_f32 v45, v45, v170, v170
	v_fma_f32 v46, v46, v170, v170
	v_fma_f32 v47, v47, v170, v170
	v_fma_f32 v40, v40, v170, v170
	v_fma_f32 v41, v41, v170, v170
	v_fma_f32 v42, v42, v170, v170
	v_fma_f32 v43, v43, v170, v170
	v_rcp_f32_e32 v44, v44
	v_rcp_f32_e32 v45, v45
	v_rcp_f32_e32 v46, v46
	v_rcp_f32_e32 v47, v47
	v_rcp_f32_e32 v40, v40
	v_rcp_f32_e32 v41, v41
	v_rcp_f32_e32 v42, v42
	v_rcp_f32_e32 v43, v43
	s_mov_b32 s8, 0xc6000
	v_pk_mul_f32 v[36:37], v[36:37], v[44:45]
	v_pk_mul_f32 v[38:39], v[38:39], v[46:47]
	v_pk_mul_f32 v[32:33], v[32:33], v[40:41]
	v_pk_mul_f32 v[34:35], v[34:35], v[42:43]
	v_cvt_pk_bf16_f32 v44, v36, v37
	v_cvt_pk_bf16_f32 v45, v38, v39
	v_cvt_pk_bf16_f32 v46, v32, v33
	v_cvt_pk_bf16_f32 v47, v34, v35
	v_lshl_add_u64 v[178:179], v[176:177], 0, s[8:9]
	global_store_dwordx4 v[178:179], v[44:47], off
	v_pk_mul_f32 v[20:21], v[28:29], v[20:21]
	v_pk_mul_f32 v[22:23], v[30:31], v[22:23]
	v_pk_mul_f32 v[16:17], v[24:25], v[16:17]
	v_pk_mul_f32 v[18:19], v[26:27], v[18:19]
	s_waitcnt lgkmcnt(1)
	v_mov_b32_e32 v150, v173
	v_pk_mul_f32 v[28:29], v[28:29], v[150:151] op_sel_hi:[1,0]
	v_pk_mul_f32 v[30:31], v[30:31], v[150:151] op_sel_hi:[1,0]
	v_pk_mul_f32 v[24:25], v[24:25], v[150:151] op_sel_hi:[1,0]
	v_pk_mul_f32 v[26:27], v[26:27], v[150:151] op_sel_hi:[1,0]
	v_exp_f32_e32 v28, v28
	v_exp_f32_e32 v29, v29
	v_exp_f32_e32 v30, v30
	v_exp_f32_e32 v31, v31
	v_exp_f32_e32 v24, v24
	v_exp_f32_e32 v25, v25
	v_exp_f32_e32 v26, v26
	v_exp_f32_e32 v27, v27
	v_fma_f32 v28, v28, v172, v172
	v_fma_f32 v29, v29, v172, v172
	v_fma_f32 v30, v30, v172, v172
	v_fma_f32 v31, v31, v172, v172
	v_fma_f32 v24, v24, v172, v172
	v_fma_f32 v25, v25, v172, v172
	v_fma_f32 v26, v26, v172, v172
	v_fma_f32 v27, v27, v172, v172
	v_rcp_f32_e32 v28, v28
	v_rcp_f32_e32 v29, v29
	v_rcp_f32_e32 v30, v30
	v_rcp_f32_e32 v31, v31
	v_rcp_f32_e32 v24, v24
	v_rcp_f32_e32 v25, v25
	v_rcp_f32_e32 v26, v26
	v_rcp_f32_e32 v27, v27
	s_mov_b32 s8, 0xdc000
	v_pk_mul_f32 v[20:21], v[20:21], v[28:29]
	v_pk_mul_f32 v[22:23], v[22:23], v[30:31]
	v_pk_mul_f32 v[16:17], v[16:17], v[24:25]
	v_pk_mul_f32 v[18:19], v[18:19], v[26:27]
	v_cvt_pk_bf16_f32 v28, v20, v21
	v_cvt_pk_bf16_f32 v29, v22, v23
	v_cvt_pk_bf16_f32 v30, v16, v17
	v_cvt_pk_bf16_f32 v31, v18, v19
	v_lshl_add_u64 v[178:179], v[176:177], 0, s[8:9]
	global_store_dwordx4 v[178:179], v[28:31], off
	v_pk_mul_f32 v[4:5], v[12:13], v[4:5]
	v_pk_mul_f32 v[6:7], v[14:15], v[6:7]
	v_pk_mul_f32 v[0:1], v[8:9], v[0:1]
	v_pk_mul_f32 v[2:3], v[10:11], v[2:3]
	s_waitcnt lgkmcnt(0)
	v_mov_b32_e32 v150, v175
	v_pk_mul_f32 v[12:13], v[12:13], v[150:151] op_sel_hi:[1,0]
	v_pk_mul_f32 v[14:15], v[14:15], v[150:151] op_sel_hi:[1,0]
	v_pk_mul_f32 v[8:9], v[8:9], v[150:151] op_sel_hi:[1,0]
	v_pk_mul_f32 v[10:11], v[10:11], v[150:151] op_sel_hi:[1,0]
	v_exp_f32_e32 v12, v12
	v_exp_f32_e32 v13, v13
	v_exp_f32_e32 v14, v14
	v_exp_f32_e32 v15, v15
	v_exp_f32_e32 v8, v8
	v_exp_f32_e32 v9, v9
	v_exp_f32_e32 v10, v10
	v_exp_f32_e32 v11, v11
	v_fma_f32 v12, v12, v174, v174
	v_fma_f32 v13, v13, v174, v174
	v_fma_f32 v14, v14, v174, v174
	v_fma_f32 v15, v15, v174, v174
	v_fma_f32 v8, v8, v174, v174
	v_fma_f32 v9, v9, v174, v174
	v_fma_f32 v10, v10, v174, v174
	v_fma_f32 v11, v11, v174, v174
	v_rcp_f32_e32 v12, v12
	v_rcp_f32_e32 v13, v13
	v_rcp_f32_e32 v14, v14
	v_rcp_f32_e32 v15, v15
	v_rcp_f32_e32 v8, v8
	v_rcp_f32_e32 v9, v9
	v_rcp_f32_e32 v10, v10
	v_rcp_f32_e32 v11, v11
	s_mov_b32 s8, 0xf2000
	v_pk_mul_f32 v[4:5], v[4:5], v[12:13]
	v_pk_mul_f32 v[6:7], v[6:7], v[14:15]
	v_pk_mul_f32 v[0:1], v[0:1], v[8:9]
	v_pk_mul_f32 v[2:3], v[2:3], v[10:11]
	v_cvt_pk_bf16_f32 v12, v4, v5
	v_cvt_pk_bf16_f32 v13, v6, v7
	v_cvt_pk_bf16_f32 v14, v0, v1
	v_cvt_pk_bf16_f32 v15, v2, v3
	v_lshl_add_u64 v[178:179], v[176:177], 0, s[8:9]
	global_store_dwordx4 v[178:179], v[12:15], off
	s_andn2_b64 vcc, exec, s[6:7]
	s_mov_b64 s[6:7], -1
	s_cbranch_vccnz .LBB0_237
	s_andn2_b64 vcc, exec, s[12:13]
	s_cbranch_vccnz .LBB0_236
	s_barrier
	s_branch .LBB0_236

; __device__ __forceinline__ unsigned cvtpk(float lo, float hi) { f32x2_t v = {lo, hi}; bf16x2_t b = __builtin_convertvector(v, bf16x2_t); return __builtin_bit_cast(unsigned, b); }
;     __device__ __forceinline__ void operator()(const f32x4 (&acc)[2][2][4][2], const Unit& u, int wr, int wc, int fr, int fq) const {
;         const int row0 = u.pm * BM + wr * 64 + fr, col0 = u.pn * 128 + wc * 32 + 8 * fq;
; #pragma unroll
;         for (int ai = 0; ai < 2; ++ai)
; #pragma unroll
;             for (int m = 0; m < 4; ++m) {
;                 const int row = row0 + ai * HALF + m * 16;
;                 const float rs = 1.0f / sqrtf(ssq_sum(ssq + (size_t)row * 16) * (1.0f / DM) + EPS);
;                 float hv[8];
; #pragma unroll
;                 for (int n = 0; n < 2; ++n)
; #pragma unroll
;                     for (int e = 0; e < 4; ++e) {
;                         const float gg = acc[ai][0][m][n][e] * rs, uu = acc[ai][1][m][n][e] * rs;
;                         const float den = 1.0f + __builtin_amdgcn_exp2f(-gg * LOG2E);
;                         hv[n * 4 + e] = gg * uu * __builtin_amdgcn_rcpf(den);
;                     }
;                 u32x4 w; w.x = cvtpk(hv[0], hv[1]); w.y = cvtpk(hv[2], hv[3]); w.z = cvtpk(hv[4], hv[5]); w.w = cvtpk(hv[6], hv[7]);
;                 *(u32x4*)(H + (size_t)row * DFF + col0) = w;
.LBB0_1054:
	v_readlane_b32 s9, v254, 7
	v_mbcnt_lo_u32_b32 v144, -1, 0
	v_mbcnt_hi_u32_b32 v144, -1, v144
	v_lshrrev_b32_e32 v145, 1, v144
	v_lshl_add_u32 v145, s9, 5, v145
	v_and_b32_e32 v146, 1, v144
	v_lshl_add_u32 v147, s8, 8, v145
	v_lshlrev_b32_e32 v147, 6, v147
	v_lshl_add_u32 v147, v146, 5, v147
	global_load_dwordx4 v[160:163], v147, s[16:17]
	global_load_dwordx4 v[164:167], v147, s[16:17] offset:16
	v_lshl_add_u32 v148, s8, 8, v152
	v_mov_b64_e32 v[146:147], s[14:15]
	v_mad_i64_i32 v[176:177], s[8:9], v148, s51, v[146:147]
	v_lshl_or_b32 v150, s2, 7, v154
	v_mov_b32_e32 v151, 0
	v_lshlrev_b64 v[150:151], 1, v[150:151]
	v_lshl_add_u64 v[176:177], v[176:177], 0, v[150:151]
	v_lshlrev_b32_e32 v145, 3, v145
	v_add_u32_e32 v145, 0x20100, v145
	v_lshlrev_b32_e32 v146, 3, v152
	v_add_u32_e32 v146, 0x20100, v146
	s_mov_b32 s9, 0
	s_waitcnt vmcnt(0)
	v_pk_add_f32 v[160:161], v[160:161], v[162:163]
	v_pk_add_f32 v[164:165], v[164:165], v[166:167]
	v_pk_add_f32 v[160:161], v[160:161], v[164:165]
	v_add_f32_e32 v160, v160, v161
	s_nop 1
	v_add_f32_dpp v160, v160, v160 quad_perm:[1,0,3,2] row_mask:0xf bank_mask:0xf
	v_fmamk_f32 v160, v160, 0x3a800000, v158
	v_rsq_f32_e32 v161, v160
	s_nop 0
	v_mul_f32_e32 v161, 0xbfb8aa3b, v161
	ds_write_b64 v145, v[160:161]
	s_waitcnt lgkmcnt(0)
	s_barrier
	ds_read_b64 v[160:161], v146 offset:0
	ds_read_b64 v[162:163], v146 offset:128
	ds_read_b64 v[164:165], v146 offset:256
	ds_read_b64 v[166:167], v146 offset:384
	ds_read_b64 v[168:169], v146 offset:1024
	ds_read_b64 v[170:171], v146 offset:1152
	ds_read_b64 v[172:173], v146 offset:1280
	ds_read_b64 v[174:175], v146 offset:1408
	v_pk_mul_f32 v[116:117], v[124:125], v[116:117]
	v_pk_mul_f32 v[118:119], v[126:127], v[118:119]
	v_pk_mul_f32 v[112:113], v[120:121], v[112:113]
	v_pk_mul_f32 v[114:115], v[122:123], v[114:115]
	s_waitcnt lgkmcnt(7)
	v_mov_b32_e32 v150, v161
	v_pk_mul_f32 v[124:125], v[124:125], v[150:151] op_sel_hi:[1,0]
	v_pk_mul_f32 v[126:127], v[126:127], v[150:151] op_sel_hi:[1,0]
	v_pk_mul_f32 v[120:121], v[120:121], v[150:151] op_sel_hi:[1,0]
	v_pk_mul_f32 v[122:123], v[122:123], v[150:151] op_sel_hi:[1,0]
	v_exp_f32_e32 v124, v124
	v_exp_f32_e32 v125, v125
	v_exp_f32_e32 v126, v126
	v_exp_f32_e32 v127, v127
	v_exp_f32_e32 v120, v120
	v_exp_f32_e32 v121, v121
	v_exp_f32_e32 v122, v122
	v_exp_f32_e32 v123, v123
	v_fma_f32 v124, v124, v160, v160
	v_fma_f32 v125, v125, v160, v160
	v_fma_f32 v126, v126, v160, v160
	v_fma_f32 v127, v127, v160, v160
	v_fma_f32 v120, v120, v160, v160
	v_fma_f32 v121, v121, v160, v160
	v_fma_f32 v122, v122, v160, v160
	v_fma_f32 v123, v123, v160, v160
	v_rcp_f32_e32 v124, v124
	v_rcp_f32_e32 v125, v125
	v_rcp_f32_e32 v126, v126
	v_rcp_f32_e32 v127, v127
	v_rcp_f32_e32 v120, v120
	v_rcp_f32_e32 v121, v121
	v_rcp_f32_e32 v122, v122
	v_rcp_f32_e32 v123, v123
	v_pk_mul_f32 v[116:117], v[116:117], v[124:125]
	v_pk_mul_f32 v[118:119], v[118:119], v[126:127]
	v_pk_mul_f32 v[112:113], v[112:113], v[120:121]
	v_pk_mul_f32 v[114:115], v[114:115], v[122:123]
	v_cvt_pk_bf16_f32 v124, v116, v117
	v_cvt_pk_bf16_f32 v125, v118, v119
	v_cvt_pk_bf16_f32 v126, v112, v113
	v_cvt_pk_bf16_f32 v127, v114, v115
	global_store_dwordx4 v[176:177], v[124:127], off
	v_pk_mul_f32 v[100:101], v[108:109], v[100:101]
	v_pk_mul_f32 v[102:103], v[110:111], v[102:103]
	v_pk_mul_f32 v[96:97], v[104:105], v[96:97]
	v_pk_mul_f32 v[98:99], v[106:107], v[98:99]
	s_waitcnt lgkmcnt(6)
	v_mov_b32_e32 v150, v163
	v_pk_mul_f32 v[108:109], v[108:109], v[150:151] op_sel_hi:[1,0]
	v_pk_mul_f32 v[110:111], v[110:111], v[150:151] op_sel_hi:[1,0]
	v_pk_mul_f32 v[104:105], v[104:105], v[150:151] op_sel_hi:[1,0]
	v_pk_mul_f32 v[106:107], v[106:107], v[150:151] op_sel_hi:[1,0]
	v_exp_f32_e32 v108, v108
	v_exp_f32_e32 v109, v109
	v_exp_f32_e32 v110, v110
	v_exp_f32_e32 v111, v111
	v_exp_f32_e32 v104, v104
	v_exp_f32_e32 v105, v105
	v_exp_f32_e32 v106, v106
	v_exp_f32_e32 v107, v107
	v_fma_f32 v108, v108, v162, v162
	v_fma_f32 v109, v109, v162, v162
	v_fma_f32 v110, v110, v162, v162
	v_fma_f32 v111, v111, v162, v162
	v_fma_f32 v104, v104, v162, v162
	v_fma_f32 v105, v105, v162, v162
	v_fma_f32 v106, v106, v162, v162
	v_fma_f32 v107, v107, v162, v162
	v_rcp_f32_e32 v108, v108
	v_rcp_f32_e32 v109, v109
	v_rcp_f32_e32 v110, v110
	v_rcp_f32_e32 v111, v111
	v_rcp_f32_e32 v104, v104
	v_rcp_f32_e32 v105, v105
	v_rcp_f32_e32 v106, v106
	v_rcp_f32_e32 v107, v107
	s_mov_b32 s8, 0x16000
	v_pk_mul_f32 v[100:101], v[100:101], v[108:109]
	v_pk_mul_f32 v[102:103], v[102:103], v[110:111]
	v_pk_mul_f32 v[96:97], v[96:97], v[104:105]
	v_pk_mul_f32 v[98:99], v[98:99], v[106:107]
	v_cvt_pk_bf16_f32 v108, v100, v101
	v_cvt_pk_bf16_f32 v109, v102, v103
	v_cvt_pk_bf16_f32 v110, v96, v97
	v_cvt_pk_bf16_f32 v111, v98, v99
	v_lshl_add_u64 v[178:179], v[176:177], 0, s[8:9]
	global_store_dwordx4 v[178:179], v[108:111], off
	v_pk_mul_f32 v[84:85], v[92:93], v[84:85]
	v_pk_mul_f32 v[86:87], v[94:95], v[86:87]
	v_pk_mul_f32 v[80:81], v[88:89], v[80:81]
	v_pk_mul_f32 v[82:83], v[90:91], v[82:83]
	s_waitcnt lgkmcnt(5)
; __device__ __forceinline__ unsigned cvtpk(float lo, float hi) { f32x2_t v = {lo, hi}; bf16x2_t b = __builtin_convertvector(v, bf16x2_t); return __builtin_bit_cast(unsigned, b); }
;     __device__ __forceinline__ void operator()(const f32x4 (&acc)[2][2][4][2], const Unit& u, int wr, int wc, int fr, int fq) const {
;     ...
;             for (int m = 0; m < 4; ++m) {
;                 const int row = row0 + ai * HALF + m * 16;
;                 const float rs = 1.0f / sqrtf(ssq_sum(ssq + (size_t)row * 16) * (1.0f / DM) + EPS);
;                 float hv[8];
; #pragma unroll
;                 for (int n = 0; n < 2; ++n)
; #pragma unroll
;                     for (int e = 0; e < 4; ++e) {
;                         const float gg = acc[ai][0][m][n][e] * rs, uu = acc[ai][1][m][n][e] * rs;
;                         const float den = 1.0f + __builtin_amdgcn_exp2f(-gg * LOG2E);
;                         hv[n * 4 + e] = gg * uu * __builtin_amdgcn_rcpf(den);
;                     }
;                 u32x4 w; w.x = cvtpk(hv[0], hv[1]); w.y = cvtpk(hv[2], hv[3]); w.z = cvtpk(hv[4], hv[5]); w.w = cvtpk(hv[6], hv[7]);
;                 *(u32x4*)(H + (size_t)row * DFF + col0) = w;
	v_mov_b32_e32 v150, v165
	v_pk_mul_f32 v[92:93], v[92:93], v[150:151] op_sel_hi:[1,0]
	v_pk_mul_f32 v[94:95], v[94:95], v[150:151] op_sel_hi:[1,0]
	v_pk_mul_f32 v[88:89], v[88:89], v[150:151] op_sel_hi:[1,0]
	v_pk_mul_f32 v[90:91], v[90:91], v[150:151] op_sel_hi:[1,0]
	v_exp_f32_e32 v92, v92
	v_exp_f32_e32 v93, v93
	v_exp_f32_e32 v94, v94
	v_exp_f32_e32 v95, v95
	v_exp_f32_e32 v88, v88
	v_exp_f32_e32 v89, v89
	v_exp_f32_e32 v90, v90
	v_exp_f32_e32 v91, v91
	v_fma_f32 v92, v92, v164, v164
	v_fma_f32 v93, v93, v164, v164
	v_fma_f32 v94, v94, v164, v164
	v_fma_f32 v95, v95, v164, v164
	v_fma_f32 v88, v88, v164, v164
	v_fma_f32 v89, v89, v164, v164
	v_fma_f32 v90, v90, v164, v164
	v_fma_f32 v91, v91, v164, v164
	v_rcp_f32_e32 v92, v92
	v_rcp_f32_e32 v93, v93
	v_rcp_f32_e32 v94, v94
	v_rcp_f32_e32 v95, v95
	v_rcp_f32_e32 v88, v88
	v_rcp_f32_e32 v89, v89
	v_rcp_f32_e32 v90, v90
	v_rcp_f32_e32 v91, v91
	s_mov_b32 s8, 0x2c000
	v_pk_mul_f32 v[84:85], v[84:85], v[92:93]
	v_pk_mul_f32 v[86:87], v[86:87], v[94:95]
	v_pk_mul_f32 v[80:81], v[80:81], v[88:89]
	v_pk_mul_f32 v[82:83], v[82:83], v[90:91]
	v_cvt_pk_bf16_f32 v92, v84, v85
	v_cvt_pk_bf16_f32 v93, v86, v87
	v_cvt_pk_bf16_f32 v94, v80, v81
	v_cvt_pk_bf16_f32 v95, v82, v83
	v_lshl_add_u64 v[178:179], v[176:177], 0, s[8:9]
	global_store_dwordx4 v[178:179], v[92:95], off
	v_pk_mul_f32 v[68:69], v[76:77], v[68:69]
	v_pk_mul_f32 v[70:71], v[78:79], v[70:71]
	v_pk_mul_f32 v[64:65], v[72:73], v[64:65]
	v_pk_mul_f32 v[66:67], v[74:75], v[66:67]
	s_waitcnt lgkmcnt(4)
	v_mov_b32_e32 v150, v167
	v_pk_mul_f32 v[76:77], v[76:77], v[150:151] op_sel_hi:[1,0]
	v_pk_mul_f32 v[78:79], v[78:79], v[150:151] op_sel_hi:[1,0]
	v_pk_mul_f32 v[72:73], v[72:73], v[150:151] op_sel_hi:[1,0]
	v_pk_mul_f32 v[74:75], v[74:75], v[150:151] op_sel_hi:[1,0]
	v_exp_f32_e32 v76, v76
	v_exp_f32_e32 v77, v77
	v_exp_f32_e32 v78, v78
	v_exp_f32_e32 v79, v79
	v_exp_f32_e32 v72, v72
	v_exp_f32_e32 v73, v73
	v_exp_f32_e32 v74, v74
	v_exp_f32_e32 v75, v75
	v_fma_f32 v76, v76, v166, v166
	v_fma_f32 v77, v77, v166, v166
	v_fma_f32 v78, v78, v166, v166
	v_fma_f32 v79, v79, v166, v166
	v_fma_f32 v72, v72, v166, v166
	v_fma_f32 v73, v73, v166, v166
	v_fma_f32 v74, v74, v166, v166
	v_fma_f32 v75, v75, v166, v166
	v_rcp_f32_e32 v76, v76
	v_rcp_f32_e32 v77, v77
	v_rcp_f32_e32 v78, v78
	v_rcp_f32_e32 v79, v79
	v_rcp_f32_e32 v72, v72
	v_rcp_f32_e32 v73, v73
	v_rcp_f32_e32 v74, v74
	v_rcp_f32_e32 v75, v75
	s_mov_b32 s8, 0x42000
	v_pk_mul_f32 v[68:69], v[68:69], v[76:77]
	v_pk_mul_f32 v[70:71], v[70:71], v[78:79]
	v_pk_mul_f32 v[64:65], v[64:65], v[72:73]
	v_pk_mul_f32 v[66:67], v[66:67], v[74:75]
	v_cvt_pk_bf16_f32 v76, v68, v69
	v_cvt_pk_bf16_f32 v77, v70, v71
	v_cvt_pk_bf16_f32 v78, v64, v65
	v_cvt_pk_bf16_f32 v79, v66, v67
	v_lshl_add_u64 v[178:179], v[176:177], 0, s[8:9]
	global_store_dwordx4 v[178:179], v[76:79], off
	v_pk_mul_f32 v[52:53], v[60:61], v[52:53]
	v_pk_mul_f32 v[54:55], v[62:63], v[54:55]
	v_pk_mul_f32 v[48:49], v[56:57], v[48:49]
	v_pk_mul_f32 v[50:51], v[58:59], v[50:51]
	s_waitcnt lgkmcnt(3)
	v_mov_b32_e32 v150, v169
	v_pk_mul_f32 v[60:61], v[60:61], v[150:151] op_sel_hi:[1,0]
	v_pk_mul_f32 v[62:63], v[62:63], v[150:151] op_sel_hi:[1,0]
	v_pk_mul_f32 v[56:57], v[56:57], v[150:151] op_sel_hi:[1,0]
	v_pk_mul_f32 v[58:59], v[58:59], v[150:151] op_sel_hi:[1,0]
	v_exp_f32_e32 v60, v60
	v_exp_f32_e32 v61, v61
	v_exp_f32_e32 v62, v62
	v_exp_f32_e32 v63, v63
	v_exp_f32_e32 v56, v56
	v_exp_f32_e32 v57, v57
	v_exp_f32_e32 v58, v58
	v_exp_f32_e32 v59, v59
	v_fma_f32 v60, v60, v168, v168
	v_fma_f32 v61, v61, v168, v168
	v_fma_f32 v62, v62, v168, v168
	v_fma_f32 v63, v63, v168, v168
	v_fma_f32 v56, v56, v168, v168
	v_fma_f32 v57, v57, v168, v168
	v_fma_f32 v58, v58, v168, v168
	v_fma_f32 v59, v59, v168, v168
	v_rcp_f32_e32 v60, v60
	v_rcp_f32_e32 v61, v61
	v_rcp_f32_e32 v62, v62
	v_rcp_f32_e32 v63, v63
	v_rcp_f32_e32 v56, v56
	v_rcp_f32_e32 v57, v57
	v_rcp_f32_e32 v58, v58
	v_rcp_f32_e32 v59, v59
	s_mov_b32 s8, 0xb0000
	v_pk_mul_f32 v[52:53], v[52:53], v[60:61]
	v_pk_mul_f32 v[54:55], v[54:55], v[62:63]
	v_pk_mul_f32 v[48:49], v[48:49], v[56:57]
	v_pk_mul_f32 v[50:51], v[50:51], v[58:59]
	v_cvt_pk_bf16_f32 v60, v52, v53
	v_cvt_pk_bf16_f32 v61, v54, v55
	v_cvt_pk_bf16_f32 v62, v48, v49
	v_cvt_pk_bf16_f32 v63, v50, v51
	v_lshl_add_u64 v[178:179], v[176:177], 0, s[8:9]
	global_store_dwordx4 v[178:179], v[60:63], off
	v_pk_mul_f32 v[36:37], v[44:45], v[36:37]
	v_pk_mul_f32 v[38:39], v[46:47], v[38:39]
	v_pk_mul_f32 v[32:33], v[40:41], v[32:33]
	v_pk_mul_f32 v[34:35], v[42:43], v[34:35]
	s_waitcnt lgkmcnt(2)
; __device__ __forceinline__ unsigned cvtpk(float lo, float hi) { f32x2_t v = {lo, hi}; bf16x2_t b = __builtin_convertvector(v, bf16x2_t); return __builtin_bit_cast(unsigned, b); }
;     __device__ __forceinline__ void operator()(const f32x4 (&acc)[2][2][4][2], const Unit& u, int wr, int wc, int fr, int fq) const {
;     ...
;             for (int m = 0; m < 4; ++m) {
;                 const int row = row0 + ai * HALF + m * 16;
;                 const float rs = 1.0f / sqrtf(ssq_sum(ssq + (size_t)row * 16) * (1.0f / DM) + EPS);
;                 float hv[8];
; #pragma unroll
;                 for (int n = 0; n < 2; ++n)
; #pragma unroll
;                     for (int e = 0; e < 4; ++e) {
;                         const float gg = acc[ai][0][m][n][e] * rs, uu = acc[ai][1][m][n][e] * rs;
;                         const float den = 1.0f + __builtin_amdgcn_exp2f(-gg * LOG2E);
;                         hv[n * 4 + e] = gg * uu * __builtin_amdgcn_rcpf(den);
;                     }
;                 u32x4 w; w.x = cvtpk(hv[0], hv[1]); w.y = cvtpk(hv[2], hv[3]); w.z = cvtpk(hv[4], hv[5]); w.w = cvtpk(hv[6], hv[7]);
;                 *(u32x4*)(H + (size_t)row * DFF + col0) = w;
	v_mov_b32_e32 v150, v171
	v_pk_mul_f32 v[44:45], v[44:45], v[150:151] op_sel_hi:[1,0]
	v_pk_mul_f32 v[46:47], v[46:47], v[150:151] op_sel_hi:[1,0]
	v_pk_mul_f32 v[40:41], v[40:41], v[150:151] op_sel_hi:[1,0]
	v_pk_mul_f32 v[42:43], v[42:43], v[150:151] op_sel_hi:[1,0]
	v_exp_f32_e32 v44, v44
	v_exp_f32_e32 v45, v45
	v_exp_f32_e32 v46, v46
	v_exp_f32_e32 v47, v47
	v_exp_f32_e32 v40, v40
	v_exp_f32_e32 v41, v41
	v_exp_f32_e32 v42, v42
	v_exp_f32_e32 v43, v43
	v_fma_f32 v44, v44, v170, v170
	v_fma_f32 v45, v45, v170, v170
	v_fma_f32 v46, v46, v170, v170
	v_fma_f32 v47, v47, v170, v170
	v_fma_f32 v40, v40, v170, v170
	v_fma_f32 v41, v41, v170, v170
	v_fma_f32 v42, v42, v170, v170
	v_fma_f32 v43, v43, v170, v170
	v_rcp_f32_e32 v44, v44
	v_rcp_f32_e32 v45, v45
	v_rcp_f32_e32 v46, v46
	v_rcp_f32_e32 v47, v47
	v_rcp_f32_e32 v40, v40
	v_rcp_f32_e32 v41, v41
	v_rcp_f32_e32 v42, v42
	v_rcp_f32_e32 v43, v43
	s_mov_b32 s8, 0xc6000
	v_pk_mul_f32 v[36:37], v[36:37], v[44:45]
	v_pk_mul_f32 v[38:39], v[38:39], v[46:47]
	v_pk_mul_f32 v[32:33], v[32:33], v[40:41]
	v_pk_mul_f32 v[34:35], v[34:35], v[42:43]
	v_cvt_pk_bf16_f32 v44, v36, v37
	v_cvt_pk_bf16_f32 v45, v38, v39
	v_cvt_pk_bf16_f32 v46, v32, v33
	v_cvt_pk_bf16_f32 v47, v34, v35
	v_lshl_add_u64 v[178:179], v[176:177], 0, s[8:9]
	global_store_dwordx4 v[178:179], v[44:47], off
	v_pk_mul_f32 v[20:21], v[28:29], v[20:21]
	v_pk_mul_f32 v[22:23], v[30:31], v[22:23]
	v_pk_mul_f32 v[16:17], v[24:25], v[16:17]
	v_pk_mul_f32 v[18:19], v[26:27], v[18:19]
	s_waitcnt lgkmcnt(1)
	v_mov_b32_e32 v150, v173
	v_pk_mul_f32 v[28:29], v[28:29], v[150:151] op_sel_hi:[1,0]
	v_pk_mul_f32 v[30:31], v[30:31], v[150:151] op_sel_hi:[1,0]
	v_pk_mul_f32 v[24:25], v[24:25], v[150:151] op_sel_hi:[1,0]
	v_pk_mul_f32 v[26:27], v[26:27], v[150:151] op_sel_hi:[1,0]
	v_exp_f32_e32 v28, v28
	v_exp_f32_e32 v29, v29
	v_exp_f32_e32 v30, v30
	v_exp_f32_e32 v31, v31
	v_exp_f32_e32 v24, v24
	v_exp_f32_e32 v25, v25
	v_exp_f32_e32 v26, v26
	v_exp_f32_e32 v27, v27
	v_fma_f32 v28, v28, v172, v172
	v_fma_f32 v29, v29, v172, v172
	v_fma_f32 v30, v30, v172, v172
	v_fma_f32 v31, v31, v172, v172
	v_fma_f32 v24, v24, v172, v172
	v_fma_f32 v25, v25, v172, v172
	v_fma_f32 v26, v26, v172, v172
	v_fma_f32 v27, v27, v172, v172
	v_rcp_f32_e32 v28, v28
	v_rcp_f32_e32 v29, v29
	v_rcp_f32_e32 v30, v30
	v_rcp_f32_e32 v31, v31
	v_rcp_f32_e32 v24, v24
	v_rcp_f32_e32 v25, v25
	v_rcp_f32_e32 v26, v26
	v_rcp_f32_e32 v27, v27
	s_mov_b32 s8, 0xdc000
	v_pk_mul_f32 v[20:21], v[20:21], v[28:29]
	v_pk_mul_f32 v[22:23], v[22:23], v[30:31]
	v_pk_mul_f32 v[16:17], v[16:17], v[24:25]
	v_pk_mul_f32 v[18:19], v[18:19], v[26:27]
	v_cvt_pk_bf16_f32 v28, v20, v21
	v_cvt_pk_bf16_f32 v29, v22, v23
	v_cvt_pk_bf16_f32 v30, v16, v17
	v_cvt_pk_bf16_f32 v31, v18, v19
	v_lshl_add_u64 v[178:179], v[176:177], 0, s[8:9]
	global_store_dwordx4 v[178:179], v[28:31], off
	v_pk_mul_f32 v[4:5], v[12:13], v[4:5]
	v_pk_mul_f32 v[6:7], v[14:15], v[6:7]
	v_pk_mul_f32 v[0:1], v[8:9], v[0:1]
	v_pk_mul_f32 v[2:3], v[10:11], v[2:3]
	s_waitcnt lgkmcnt(0)
	v_mov_b32_e32 v150, v175
	v_pk_mul_f32 v[12:13], v[12:13], v[150:151] op_sel_hi:[1,0]
	v_pk_mul_f32 v[14:15], v[14:15], v[150:151] op_sel_hi:[1,0]
	v_pk_mul_f32 v[8:9], v[8:9], v[150:151] op_sel_hi:[1,0]
	v_pk_mul_f32 v[10:11], v[10:11], v[150:151] op_sel_hi:[1,0]
	v_exp_f32_e32 v12, v12
	v_exp_f32_e32 v13, v13
	v_exp_f32_e32 v14, v14
	v_exp_f32_e32 v15, v15
	v_exp_f32_e32 v8, v8
	v_exp_f32_e32 v9, v9
	v_exp_f32_e32 v10, v10
	v_exp_f32_e32 v11, v11
	v_fma_f32 v12, v12, v174, v174
	v_fma_f32 v13, v13, v174, v174
	v_fma_f32 v14, v14, v174, v174
	v_fma_f32 v15, v15, v174, v174
	v_fma_f32 v8, v8, v174, v174
	v_fma_f32 v9, v9, v174, v174
	v_fma_f32 v10, v10, v174, v174
	v_fma_f32 v11, v11, v174, v174
	v_rcp_f32_e32 v12, v12
	v_rcp_f32_e32 v13, v13
	v_rcp_f32_e32 v14, v14
	v_rcp_f32_e32 v15, v15
	v_rcp_f32_e32 v8, v8
	v_rcp_f32_e32 v9, v9
	v_rcp_f32_e32 v10, v10
	v_rcp_f32_e32 v11, v11
	s_mov_b32 s8, 0xf2000
	v_pk_mul_f32 v[4:5], v[4:5], v[12:13]
	v_pk_mul_f32 v[6:7], v[6:7], v[14:15]
	v_pk_mul_f32 v[0:1], v[0:1], v[8:9]
	v_pk_mul_f32 v[2:3], v[2:3], v[10:11]
	v_cvt_pk_bf16_f32 v12, v4, v5
	v_cvt_pk_bf16_f32 v13, v6, v7
	v_cvt_pk_bf16_f32 v14, v0, v1
	v_cvt_pk_bf16_f32 v15, v2, v3
	v_lshl_add_u64 v[178:179], v[176:177], 0, s[8:9]
	global_store_dwordx4 v[178:179], v[12:15], off
	s_andn2_b64 vcc, exec, s[6:7]
	s_mov_b64 s[6:7], -1
	s_cbranch_vccnz .LBB0_1047
	s_andn2_b64 vcc, exec, s[12:13]
	s_cbranch_vccnz .LBB0_1046
	s_barrier
	s_branch .LBB0_1046
